# gmt_unit: w_fourier block staged through LDS with one batched load instead of 64 serialized loads (on top of batched P0 transposes)
# baseline (speedup 1.0000x reference)
; __device__ __forceinline__ void gmt_unit(const Args& a, LAS unsigned char* lds, int unit, int tid) {
;     ...
;     if (tid < 64) { float sn, cs; sincospif((float)tid * (1.f / 32.f), &sn, &cs); tab[2 * tid] = cs; tab[2 * tid + 1] = sn; }
;     __syncthreads();
;     const int g = unit >> 2, d = 16 * (unit & 3) + (tid >> 5), c32 = tid & 31;
;     float acc[4] = {0.f, 0.f, 0.f, 0.f};
;     for (int l = 0; l < 64; ++l) { const float w = a.wf[(size_t)(g * 64 + l) * 64 + d];
; #pragma unroll
;         for (int e = 0; e < 4; ++e) { const int cc = c32 * 4 + e, c = cc & 63, idx = (l * c) & 63; acc[e] += w * (cc < 64 ? tab[2 * idx] : -tab[2 * idx + 1]); } }
.LBB0_20:
	s_and_saveexec_b64 s[4:5], vcc
	ds_write_b64 v15, v[0:1]
	s_or_b64 exec, exec, s[4:5]
	s_and_b32 s4, s8, 0xffffffc0
	s_ashr_i32 s5, s4, 31
	s_lshl_b64 s[4:5], s[4:5], 8
	s_and_b32 s6, s8, 48
	s_waitcnt lgkmcnt(0)
	s_add_u32 s4, s46, s4
	v_add_lshl_u32 v2, v36, s6, 2
	s_addc_u32 s5, s47, s5
	v_lshl_add_u64 v[6:7], s[4:5], 0, v[2:3]
	s_lshl_b32 s100, s6, 2
	s_add_u32 s100, s4, s100
	s_addc_u32 s101, s5, 0
	v_lshrrev_b32_e32 v241, 4, v178
	v_and_b32_e32 v242, 15, v178
	v_lshlrev_b32_e32 v241, 8, v241
	v_lshl_add_u32 v241, v242, 2, v241
	v_add_u32_e32 v239, 0x2000, v241
	global_load_dword v242, v241, s[100:101]
	global_load_dword v240, v239, s[100:101]
	v_lshlrev_b32_e32 v238, 2, v178
	v_lshlrev_b32_e32 v237, 2, v36
	v_add_u32_e32 v237, 0x400, v237
	s_waitcnt vmcnt(0)
	ds_write_b32 v238, v242 offset:1024
	ds_write_b32 v238, v240 offset:3072
	v_mov_b32_e32 v2, 0
	s_mov_b64 s[4:5], 0
	v_mov_b32_e32 v19, 0
	v_mov_b32_e32 v20, 0
	v_mov_b32_e32 v21, 0
	v_mov_b32_e32 v22, 0
	v_mov_b32_e32 v16, 0
	v_mov_b32_e32 v17, 0
	v_mov_b32_e32 v18, 0
	s_waitcnt lgkmcnt(0)
	s_barrier
	s_branch .LBB0_24
.LBB0_23:
	s_or_b64 exec, exec, s[6:7]
	s_add_u32 s4, s4, 0x200
	v_add_u32_e32 v237, 0x80, v237
	s_waitcnt vmcnt(1) lgkmcnt(0)
	v_fmac_f32_e32 v2, v23, v24
	v_fmac_f32_e32 v16, v23, v25
	v_fmac_f32_e32 v17, v23, v26
	v_fmac_f32_e32 v18, v23, v27
	s_addc_u32 s5, s5, 0
	s_waitcnt vmcnt(0)
	v_fmac_f32_e32 v2, v8, v9
	v_fmac_f32_e32 v16, v8, v28
	v_fmac_f32_e32 v17, v8, v29
	v_fmac_f32_e32 v18, v8, v30
	v_add_u32_e32 v22, v22, v12
	v_add_u32_e32 v21, v21, v13
	v_add_u32_e32 v20, v20, v14
	s_cmpk_lg_i32 s4, 0x4000
	v_add_u32_e32 v19, v19, v38
	s_cbranch_scc0 .LBB0_19
.LBB0_24:
	v_lshl_add_u64 v[8:9], v[6:7], 0, s[4:5]
	ds_read_b32 v23, v237
	v_and_b32_e32 v24, 0x1c0, v19
	v_add_u32_e32 v25, 0, v24
	s_and_saveexec_b64 s[6:7], s[0:1]
	s_xor_b64 s[6:7], exec, s[6:7]
	s_cbranch_execz .LBB0_26
	ds_read_b32 v24, v25 offset:4
	s_waitcnt lgkmcnt(0)
	v_xor_b32_e32 v24, 0x80000000, v24

; __device__ __forceinline__ void gmt_unit(const Args& a, LAS unsigned char* lds, int unit, int tid) {
;     ...
;     for (int l = 0; l < 64; ++l) { const float w = a.wf[(size_t)(g * 64 + l) * 64 + d];
; #pragma unroll
;         for (int e = 0; e < 4; ++e) { const int cc = c32 * 4 + e, c = cc & 63, idx = (l * c) & 63; acc[e] += w * (cc < 64 ? tab[2 * idx] : -tab[2 * idx + 1]); } }
.LBB0_38:
	s_andn2_saveexec_b64 s[6:7], s[6:7]
	ds_read_b32 v27, v28
	s_or_b64 exec, exec, s[6:7]
	ds_read_b32 v8, v237 offset:64
	v_add_u32_e32 v9, v11, v19
	v_and_b32_e32 v9, 0x1e0, v9
	v_add_u32_e32 v28, 0, v9
	s_and_saveexec_b64 s[6:7], s[0:1]
	s_xor_b64 s[6:7], exec, s[6:7]
	s_cbranch_execz .LBB0_42
	ds_read_b32 v9, v28 offset:4
	s_waitcnt lgkmcnt(0)
	v_xor_b32_e32 v9, 0x80000000, v9

; #define LAS __attribute__((address_space(3)))
; __global__ void __launch_bounds__(512, 2) mega_fwd(Args a) {
;     extern __shared__ __attribute__((aligned(16))) unsigned char lds_raw[];
;     LAS unsigned char* lds = (LAS unsigned char*)lds_raw;
;     cg::grid_group grid = cg::this_grid();
;     const int tid = threadIdx.x, lane = tid & 63, wave = __builtin_amdgcn_readfirstlane(tid >> 6);
	.amdhsa_kernel _Z8mega_fwd4Args
		.amdhsa_group_segment_fixed_size 0
		.amdhsa_private_segment_fixed_size 0
		.amdhsa_kernarg_size 328
		.amdhsa_user_sgpr_count 2
		.amdhsa_user_sgpr_dispatch_ptr 0
		.amdhsa_user_sgpr_queue_ptr 0
		.amdhsa_user_sgpr_kernarg_segment_ptr 1
		.amdhsa_user_sgpr_dispatch_id 0
		.amdhsa_user_sgpr_kernarg_preload_length 0
		.amdhsa_user_sgpr_kernarg_preload_offset 0
		.amdhsa_user_sgpr_private_segment_size 0
		.amdhsa_uses_dynamic_stack 0
		.amdhsa_enable_private_segment 0
		.amdhsa_system_sgpr_workgroup_id_x 1
		.amdhsa_system_sgpr_workgroup_id_y 0
		.amdhsa_system_sgpr_workgroup_id_z 0
		.amdhsa_system_sgpr_workgroup_info 0
		.amdhsa_system_vgpr_workitem_id 2
		.amdhsa_next_free_vgpr 243
		.amdhsa_next_free_sgpr 102
		.amdhsa_accum_offset 244
		.amdhsa_reserve_vcc 1
		.amdhsa_float_round_mode_32 0
		.amdhsa_float_round_mode_16_64 0
		.amdhsa_float_denorm_mode_32 3
		.amdhsa_float_denorm_mode_16_64 3
		.amdhsa_dx10_clamp 1
		.amdhsa_ieee_mode 1
		.amdhsa_fp16_overflow 0
		.amdhsa_tg_split 0
		.amdhsa_exception_fp_ieee_invalid_op 0
		.amdhsa_exception_fp_denorm_src 0
		.amdhsa_exception_fp_ieee_div_zero 0
		.amdhsa_exception_fp_ieee_overflow 0
		.amdhsa_exception_fp_ieee_underflow 0
		.amdhsa_exception_fp_ieee_inexact 0
		.amdhsa_exception_int_div_zero 0
	.end_amdhsa_kernel

; #define LAS __attribute__((address_space(3)))
; __global__ void __launch_bounds__(512, 2) mega_fwd(Args a) {
;     extern __shared__ __attribute__((aligned(16))) unsigned char lds_raw[];
;     LAS unsigned char* lds = (LAS unsigned char*)lds_raw;
;     cg::grid_group grid = cg::this_grid();
;     const int tid = threadIdx.x, lane = tid & 63, wave = __builtin_amdgcn_readfirstlane(tid >> 6);
amdhsa.kernels:
  - .agpr_count:     0
    .args:
      - .offset:         0
        .size:           72
        .value_kind:     by_value
      - .offset:         72
        .size:           4
        .value_kind:     hidden_block_count_x
      - .offset:         76
        .size:           4
        .value_kind:     hidden_block_count_y
      - .offset:         80
        .size:           4
        .value_kind:     hidden_block_count_z
      - .offset:         84
        .size:           2
        .value_kind:     hidden_group_size_x
      - .offset:         86
        .size:           2
        .value_kind:     hidden_group_size_y
      - .offset:         88
        .size:           2
        .value_kind:     hidden_group_size_z
      - .offset:         90
        .size:           2
        .value_kind:     hidden_remainder_x
      - .offset:         92
        .size:           2
        .value_kind:     hidden_remainder_y
      - .offset:         94
        .size:           2
        .value_kind:     hidden_remainder_z
      - .offset:         112
        .size:           8
        .value_kind:     hidden_global_offset_x
      - .offset:         120
        .size:           8
        .value_kind:     hidden_global_offset_y
      - .offset:         128
        .size:           8
        .value_kind:     hidden_global_offset_z
      - .offset:         136
        .size:           2
        .value_kind:     hidden_grid_dims
      - .offset:         160
        .size:           8
        .value_kind:     hidden_multigrid_sync_arg
      - .offset:         192
        .size:           4
        .value_kind:     hidden_dynamic_lds_size
    .group_segment_fixed_size: 0
    .kernarg_segment_align: 8
    .kernarg_segment_size: 328
    .language:       OpenCL C
    .language_version:
      - 2
      - 0
    .max_flat_workgroup_size: 512
    .name:           _Z8mega_fwd4Args
    .private_segment_fixed_size: 0
    .sgpr_count:     108
    .sgpr_spill_count: 0
    .symbol:         _Z8mega_fwd4Args.kd
    .uniform_work_group_size: 1
    .uses_dynamic_stack: false
    .vgpr_count:     243
    .vgpr_spill_count: 0
    .wavefront_size: 64
